# DF epilogue: 128 two-byte stores per lane replaced by per-wave LDS image + 16 dwordx4 stores (on top of read pipelining and batched reductions)
# baseline (speedup 1.0000x reference)
; template <bool FIXED>
; __device__ __forceinline__ void df_unit(LAS char* lds, bf16_t* QKV, const float* gsub, float lam, float post, int b, int h, int qb, int wave0, float mfix2) {
;     ...
; #pragma unroll
;         for (int d = 0; d < 8; ++d)
; #pragma unroll
;             for (int r = 0; r < 16; ++r) { const float v = o[d][r] * rli[r] - xch[(d * 16 + r) * 64]; o[d][r] = v; ssq[r] += v * v; }
.LBB0_154:
	s_cmpk_gt_u32 s16, 0xff
	s_waitcnt lgkmcnt(0)
	s_barrier
	s_cbranch_scc1 .LBB0_156
	ds_read2st64_b32 v[180:181], v174 offset1:1
	ds_read2st64_b32 v[182:183], v174 offset0:10 offset1:11
	ds_read2st64_b32 v[184:185], v174 offset0:2 offset1:3
	ds_read2st64_b32 v[186:187], v174 offset0:4 offset1:5
	ds_read2st64_b32 v[188:189], v174 offset0:6 offset1:7
	ds_read2st64_b32 v[190:191], v174 offset0:8 offset1:9
	ds_read2st64_b32 v[192:193], v174 offset0:12 offset1:13
	ds_read2st64_b32 v[194:195], v174 offset0:14 offset1:15
	ds_read2st64_b32 v[196:197], v174 offset0:16 offset1:17
	ds_read2st64_b32 v[198:199], v174 offset0:18 offset1:19
	ds_read2st64_b32 v[200:201], v174 offset0:20 offset1:21
	ds_read2st64_b32 v[206:207], v174 offset0:22 offset1:23
	ds_read2st64_b32 v[208:209], v174 offset0:24 offset1:25
	ds_read2st64_b32 v[210:211], v174 offset0:26 offset1:27
	s_movk_i32 s0, 0x6000
	s_waitcnt lgkmcnt(13)
	v_fma_f32 v135, v114, v0, -v180
	v_fma_f32 v131, v115, v136, -v181
	ds_read2st64_b32 v[212:213], v174 offset0:28 offset1:29
	s_waitcnt lgkmcnt(12)
	v_fma_f32 v132, v116, v137, -v184
	v_fma_f32 v117, v117, v138, -v185
	ds_read2st64_b32 v[214:215], v174 offset0:30 offset1:31
	s_waitcnt lgkmcnt(12)
	v_fma_f32 v130, v118, v139, -v186
	v_fma_f32 v115, v119, v141, -v187
	ds_read2st64_b32 v[218:219], v174 offset0:32 offset1:33
	s_waitcnt lgkmcnt(12)
	v_fma_f32 v134, v120, v140, -v188
	v_fma_f32 v119, v121, v142, -v189
	ds_read2st64_b32 v[220:221], v174 offset0:34 offset1:35
	v_fma_f32 v118, v125, v145, -v183
	s_waitcnt lgkmcnt(12)
	v_fma_f32 v133, v122, v144, -v190
	v_fma_f32 v120, v123, v146, -v191
	v_fma_f32 v123, v124, v143, -v182
	ds_read2st64_b32 v[226:227], v174 offset0:36 offset1:37
	s_waitcnt lgkmcnt(12)
	v_fma_f32 v122, v126, v167, -v192
	v_fma_f32 v116, v127, v169, -v193
	ds_read2st64_b32 v[228:229], v174 offset0:38 offset1:39
	ds_read2st64_b32 v[234:235], v174 offset0:40 offset1:41
	s_waitcnt lgkmcnt(13)
	v_fma_f32 v121, v129, v173, -v195
	s_waitcnt lgkmcnt(12)
	v_fma_f32 v114, v98, v0, -v196
	v_fma_f32 v98, v99, v136, -v197
	ds_read2st64_b32 v[236:237], v174 offset0:42 offset1:43
	v_fma_f32 v124, v128, v170, -v194
	v_mul_f32_e32 v179, v114, v114
	v_fmac_f32_e32 v179, v135, v135
	v_mul_f32_e32 v178, v98, v98
	s_waitcnt lgkmcnt(12)
	v_fma_f32 v100, v100, v137, -v198
	v_fma_f32 v99, v101, v138, -v199
	ds_read2st64_b32 v[238:239], v174 offset0:44 offset1:45
	v_fmac_f32_e32 v178, v131, v131
	v_mul_f32_e32 v177, v100, v100
	v_fmac_f32_e32 v177, v132, v132
	v_mul_f32_e32 v176, v99, v99
	s_waitcnt lgkmcnt(12)
	v_fma_f32 v102, v102, v139, -v200
	v_fma_f32 v101, v103, v141, -v201
	ds_read2st64_b32 v[240:241], v174 offset0:46 offset1:47
	v_fmac_f32_e32 v176, v117, v117
	v_mul_f32_e32 v175, v102, v102
	v_fmac_f32_e32 v175, v130, v130
	v_mul_f32_e32 v171, v101, v101
	s_waitcnt lgkmcnt(12)
	v_fma_f32 v104, v104, v140, -v206
	v_fma_f32 v103, v105, v142, -v207
	ds_read2st64_b32 v[242:243], v174 offset0:48 offset1:49
	v_fmac_f32_e32 v171, v115, v115
	v_mul_f32_e32 v172, v104, v104
	v_fmac_f32_e32 v172, v134, v134
	v_mul_f32_e32 v168, v103, v103
	s_waitcnt lgkmcnt(12)
	v_fma_f32 v106, v106, v144, -v208
	v_fma_f32 v105, v107, v146, -v209
	ds_read2st64_b32 v[244:245], v174 offset0:50 offset1:51
	v_fmac_f32_e32 v168, v119, v119
	v_mul_f32_e32 v166, v106, v106
	v_fmac_f32_e32 v166, v133, v133
	v_mul_f32_e32 v161, v105, v105
	s_waitcnt lgkmcnt(12)
	v_fma_f32 v108, v108, v143, -v210
	v_fma_f32 v107, v109, v145, -v211
	ds_read2st64_b32 v[246:247], v174 offset0:52 offset1:53
	v_fmac_f32_e32 v161, v120, v120
	v_mul_f32_e32 v154, v108, v108
	v_fmac_f32_e32 v154, v123, v123
	v_mul_f32_e32 v147, v107, v107
	s_waitcnt lgkmcnt(12)
	v_fma_f32 v110, v110, v167, -v212
	v_fma_f32 v109, v111, v169, -v213
	ds_read2st64_b32 v[248:249], v174 offset0:54 offset1:55
	v_fmac_f32_e32 v147, v118, v118
	v_mul_f32_e32 v149, v110, v110
	v_fmac_f32_e32 v149, v122, v122
	v_mul_f32_e32 v148, v109, v109
	s_waitcnt lgkmcnt(12)
	v_fma_f32 v112, v112, v170, -v214
	v_fma_f32 v113, v113, v173, -v215
	ds_read2st64_b32 v[180:181], v174 offset0:56 offset1:57
	v_fmac_f32_e32 v148, v116, v116
	v_mul_f32_e32 v158, v112, v112
	v_fmac_f32_e32 v158, v124, v124
	v_mul_f32_e32 v156, v113, v113
	s_waitcnt lgkmcnt(12)
	v_fma_f32 v111, v82, v0, -v218
	v_fma_f32 v82, v83, v136, -v219
	ds_read2st64_b32 v[184:185], v174 offset0:58 offset1:59
	v_fmac_f32_e32 v179, v111, v111
	v_fmac_f32_e32 v178, v82, v82
	v_fmac_f32_e32 v156, v121, v121
	s_waitcnt lgkmcnt(12)
	v_fma_f32 v84, v84, v137, -v220
	v_fma_f32 v83, v85, v138, -v221
	ds_read2st64_b32 v[186:187], v174 offset0:60 offset1:61
	v_fmac_f32_e32 v177, v84, v84
	v_fmac_f32_e32 v176, v83, v83
	s_waitcnt lgkmcnt(12)
	v_fma_f32 v86, v86, v139, -v226
	v_fma_f32 v85, v87, v141, -v227
	ds_read2st64_b32 v[188:189], v174 offset0:62 offset1:63
	v_fmac_f32_e32 v175, v86, v86
	v_fmac_f32_e32 v171, v85, v85
	s_waitcnt lgkmcnt(12)
	v_fma_f32 v88, v88, v140, -v228
	v_fma_f32 v87, v89, v142, -v229
	ds_read2st64_b32 v[190:191], v174 offset0:64 offset1:65
	v_fmac_f32_e32 v172, v88, v88
	v_fmac_f32_e32 v168, v87, v87
	s_waitcnt lgkmcnt(12)
	v_fma_f32 v90, v90, v144, -v234
	v_fma_f32 v89, v91, v146, -v235
	ds_read2st64_b32 v[182:183], v174 offset0:66 offset1:67
	v_fmac_f32_e32 v166, v90, v90
	v_fmac_f32_e32 v161, v89, v89
	s_waitcnt lgkmcnt(12)
	v_fma_f32 v92, v92, v143, -v236
	v_fma_f32 v91, v93, v145, -v237
	ds_read2st64_b32 v[192:193], v174 offset0:68 offset1:69
	v_fmac_f32_e32 v154, v92, v92
	v_fmac_f32_e32 v147, v91, v91
	s_waitcnt lgkmcnt(12)
	v_fma_f32 v94, v94, v167, -v238
	v_fma_f32 v93, v95, v169, -v239
	ds_read2st64_b32 v[196:197], v174 offset0:70 offset1:71
	v_fmac_f32_e32 v149, v94, v94
	v_fmac_f32_e32 v148, v93, v93
	s_waitcnt lgkmcnt(12)
; template <bool FIXED>
; __device__ __forceinline__ void df_unit(LAS char* lds, bf16_t* QKV, const float* gsub, float lam, float post, int b, int h, int qb, int wave0, float mfix2) {
;     ...
;         for (int d = 0; d < 8; ++d)
; #pragma unroll
;             for (int r = 0; r < 16; ++r) { const float v = o[d][r] * rli[r] - xch[(d * 16 + r) * 64]; o[d][r] = v; ssq[r] += v * v; }
	v_fma_f32 v125, v96, v170, -v240
	v_fma_f32 v96, v97, v173, -v241
	ds_read2st64_b32 v[194:195], v174 offset0:72 offset1:73
	v_fmac_f32_e32 v158, v125, v125
	v_fmac_f32_e32 v156, v96, v96
	s_waitcnt lgkmcnt(12)
	v_fma_f32 v95, v66, v0, -v242
	v_fma_f32 v66, v67, v136, -v243
	ds_read2st64_b32 v[198:199], v174 offset0:74 offset1:75
	v_fmac_f32_e32 v179, v95, v95
	v_fmac_f32_e32 v178, v66, v66
	s_waitcnt lgkmcnt(12)
	v_fma_f32 v68, v68, v137, -v244
	v_fma_f32 v67, v69, v138, -v245
	ds_read2st64_b32 v[200:201], v174 offset0:76 offset1:77
	v_fmac_f32_e32 v177, v68, v68
	v_fmac_f32_e32 v176, v67, v67
	s_waitcnt lgkmcnt(12)
	v_fma_f32 v70, v70, v139, -v246
	v_fma_f32 v69, v71, v141, -v247
	ds_read2st64_b32 v[206:207], v174 offset0:78 offset1:79
	v_fmac_f32_e32 v175, v70, v70
	v_fmac_f32_e32 v171, v69, v69
	s_waitcnt lgkmcnt(12)
	v_fma_f32 v72, v72, v140, -v248
	v_fma_f32 v71, v73, v142, -v249
	ds_read2st64_b32 v[208:209], v174 offset0:80 offset1:81
	v_fmac_f32_e32 v172, v72, v72
	v_fmac_f32_e32 v168, v71, v71
	s_waitcnt lgkmcnt(12)
	v_fma_f32 v74, v74, v144, -v180
	v_fma_f32 v73, v75, v146, -v181
	ds_read2st64_b32 v[210:211], v174 offset0:82 offset1:83
	v_fmac_f32_e32 v166, v74, v74
	v_fmac_f32_e32 v161, v73, v73
	s_waitcnt lgkmcnt(12)
	v_fma_f32 v76, v76, v143, -v184
	v_fma_f32 v75, v77, v145, -v185
	ds_read2st64_b32 v[212:213], v174 offset0:84 offset1:85
	v_fmac_f32_e32 v154, v76, v76
	v_fmac_f32_e32 v147, v75, v75
	s_waitcnt lgkmcnt(12)
	v_fma_f32 v78, v78, v167, -v186
	v_fma_f32 v77, v79, v169, -v187
	ds_read2st64_b32 v[214:215], v174 offset0:86 offset1:87
	v_fmac_f32_e32 v149, v78, v78
	v_fmac_f32_e32 v148, v77, v77
	s_waitcnt lgkmcnt(12)
	v_fma_f32 v97, v80, v170, -v188
	v_fma_f32 v80, v81, v173, -v189
	ds_read2st64_b32 v[218:219], v174 offset0:88 offset1:89
	v_fmac_f32_e32 v158, v97, v97
	v_fmac_f32_e32 v156, v80, v80
	s_waitcnt lgkmcnt(12)
	v_fma_f32 v79, v50, v0, -v190
	v_fma_f32 v50, v51, v136, -v191
	ds_read2st64_b32 v[220:221], v174 offset0:90 offset1:91
	v_fmac_f32_e32 v179, v79, v79
	v_fmac_f32_e32 v178, v50, v50
	s_waitcnt lgkmcnt(12)
	v_fma_f32 v52, v52, v137, -v182
	v_fma_f32 v51, v53, v138, -v183
	ds_read2st64_b32 v[226:227], v174 offset0:92 offset1:93
	v_fmac_f32_e32 v177, v52, v52
	v_fmac_f32_e32 v176, v51, v51
	s_waitcnt lgkmcnt(12)
	v_fma_f32 v54, v54, v139, -v192
	v_fma_f32 v53, v55, v141, -v193
	ds_read2st64_b32 v[228:229], v174 offset0:94 offset1:95
	v_fmac_f32_e32 v175, v54, v54
	v_fmac_f32_e32 v171, v53, v53
	s_waitcnt lgkmcnt(12)
	v_fma_f32 v56, v56, v140, -v196
	v_fma_f32 v55, v57, v142, -v197
	ds_read2st64_b32 v[234:235], v174 offset0:96 offset1:97
	v_fmac_f32_e32 v172, v56, v56
	v_fmac_f32_e32 v168, v55, v55
	s_waitcnt lgkmcnt(12)
	v_fma_f32 v58, v58, v144, -v194
	v_fma_f32 v57, v59, v146, -v195
	ds_read2st64_b32 v[236:237], v174 offset0:98 offset1:99
	v_fmac_f32_e32 v166, v58, v58
	v_fmac_f32_e32 v161, v57, v57
	s_waitcnt lgkmcnt(12)
	v_fma_f32 v60, v60, v143, -v198
	v_fma_f32 v59, v61, v145, -v199
	ds_read2st64_b32 v[238:239], v174 offset0:100 offset1:101
	v_fmac_f32_e32 v154, v60, v60
	v_fmac_f32_e32 v147, v59, v59
	s_waitcnt lgkmcnt(12)
	v_fma_f32 v62, v62, v167, -v200
	v_fma_f32 v61, v63, v169, -v201
	ds_read2st64_b32 v[240:241], v174 offset0:102 offset1:103
	v_fmac_f32_e32 v149, v62, v62
	v_fmac_f32_e32 v148, v61, v61
	s_waitcnt lgkmcnt(12)
	v_fma_f32 v81, v64, v170, -v206
	v_fma_f32 v64, v65, v173, -v207
	ds_read2st64_b32 v[242:243], v174 offset0:104 offset1:105
	v_fmac_f32_e32 v158, v81, v81
	v_fmac_f32_e32 v156, v64, v64
	s_waitcnt lgkmcnt(12)
	v_fma_f32 v63, v34, v0, -v208
	v_fma_f32 v34, v35, v136, -v209
	ds_read2st64_b32 v[244:245], v174 offset0:106 offset1:107
	v_fmac_f32_e32 v179, v63, v63
	v_fmac_f32_e32 v178, v34, v34
	s_waitcnt lgkmcnt(12)
	v_fma_f32 v36, v36, v137, -v210
	v_fma_f32 v35, v37, v138, -v211
	ds_read2st64_b32 v[246:247], v174 offset0:108 offset1:109
	v_fmac_f32_e32 v177, v36, v36
	v_fmac_f32_e32 v176, v35, v35
	s_waitcnt lgkmcnt(12)
	v_fma_f32 v38, v38, v139, -v212
	v_fma_f32 v37, v39, v141, -v213
	ds_read2st64_b32 v[248:249], v174 offset0:110 offset1:111
	v_fmac_f32_e32 v175, v38, v38
	v_fmac_f32_e32 v171, v37, v37
	s_waitcnt lgkmcnt(12)
	v_fma_f32 v40, v40, v140, -v214
	v_fma_f32 v39, v41, v142, -v215
	ds_read2st64_b32 v[180:181], v174 offset0:112 offset1:113
	v_fmac_f32_e32 v172, v40, v40
	v_fmac_f32_e32 v168, v39, v39
	s_waitcnt lgkmcnt(12)
	v_fma_f32 v42, v42, v144, -v218
	v_fma_f32 v41, v43, v146, -v219
	ds_read2st64_b32 v[184:185], v174 offset0:114 offset1:115
	v_fmac_f32_e32 v166, v42, v42
	v_fmac_f32_e32 v161, v41, v41
	s_waitcnt lgkmcnt(12)
	v_fma_f32 v44, v44, v143, -v220
	v_fma_f32 v43, v45, v145, -v221
	ds_read2st64_b32 v[186:187], v174 offset0:116 offset1:117
	v_fmac_f32_e32 v154, v44, v44
	v_fmac_f32_e32 v147, v43, v43
	s_waitcnt lgkmcnt(12)
	v_fma_f32 v46, v46, v167, -v226
	v_fma_f32 v45, v47, v169, -v227
	ds_read2st64_b32 v[188:189], v174 offset0:118 offset1:119
	v_fmac_f32_e32 v149, v46, v46
	v_fmac_f32_e32 v148, v45, v45
	s_waitcnt lgkmcnt(12)
	v_fma_f32 v65, v48, v170, -v228
	v_fma_f32 v49, v49, v173, -v229
	ds_read2st64_b32 v[190:191], v174 offset0:120 offset1:121
	v_fmac_f32_e32 v158, v65, v65
	v_fmac_f32_e32 v156, v49, v49
	s_waitcnt lgkmcnt(12)
	v_fma_f32 v48, v18, v0, -v234
	v_fma_f32 v47, v19, v136, -v235
	ds_read2st64_b32 v[182:183], v174 offset0:122 offset1:123
	v_fmac_f32_e32 v179, v48, v48
	v_fmac_f32_e32 v178, v47, v47
	s_waitcnt lgkmcnt(12)
	v_fma_f32 v127, v20, v137, -v236
	v_fma_f32 v126, v21, v138, -v237
	ds_read2st64_b32 v[192:193], v174 offset0:124 offset1:125
	v_fmac_f32_e32 v177, v127, v127
	v_fmac_f32_e32 v176, v126, v126
	s_waitcnt lgkmcnt(12)
; template <bool FIXED>
; __device__ __forceinline__ void df_unit(LAS char* lds, bf16_t* QKV, const float* gsub, float lam, float post, int b, int h, int qb, int wave0, float mfix2) {
;     ...
;         for (int d = 0; d < 8; ++d)
; #pragma unroll
;             for (int r = 0; r < 16; ++r) { const float v = o[d][r] * rli[r] - xch[(d * 16 + r) * 64]; o[d][r] = v; ssq[r] += v * v; }
; #pragma unroll
;         for (int r = 0; r < 16; ++r) { float s = ssq[r]; s = xsum<1>(s); s = xsum<2>(s); s = xsum<4>(s); s = xsum<8>(s); s = xsum<16>(s);
	v_fma_f32 v129, v22, v139, -v238
	v_fma_f32 v128, v23, v141, -v239
	ds_read2st64_b32 v[196:197], v174 offset0:126 offset1:127
	v_fmac_f32_e32 v175, v129, v129
	v_fmac_f32_e32 v171, v128, v128
	s_waitcnt lgkmcnt(12)
	v_fma_f32 v151, v24, v140, -v240
	v_fma_f32 v150, v25, v142, -v241
	v_fmac_f32_e32 v172, v151, v151
	v_fmac_f32_e32 v168, v150, v150
	s_waitcnt lgkmcnt(11)
	v_fma_f32 v153, v26, v144, -v242
	v_fma_f32 v152, v27, v146, -v243
	v_fmac_f32_e32 v166, v153, v153
	v_fmac_f32_e32 v161, v152, v152
	s_waitcnt lgkmcnt(10)
	v_fma_f32 v157, v28, v143, -v244
	v_fma_f32 v155, v29, v145, -v245
	v_fmac_f32_e32 v154, v157, v157
	v_fmac_f32_e32 v147, v155, v155
	s_waitcnt lgkmcnt(9)
	v_fma_f32 v160, v30, v167, -v246
	v_fma_f32 v159, v31, v169, -v247
	v_fmac_f32_e32 v149, v160, v160
	v_fmac_f32_e32 v148, v159, v159
	s_waitcnt lgkmcnt(8)
	v_fma_f32 v164, v32, v170, -v248
	v_fma_f32 v163, v33, v173, -v249
	v_fmac_f32_e32 v158, v164, v164
	v_fmac_f32_e32 v156, v163, v163
	s_waitcnt lgkmcnt(7)
	v_fma_f32 v162, v2, v0, -v180
	v_fma_f32 v136, v3, v136, -v181
	v_fmac_f32_e32 v179, v162, v162
	v_fmac_f32_e32 v178, v136, v136
	v_mov_b32_e32 v19, v1
	s_waitcnt lgkmcnt(6)
	v_fma_f32 v165, v4, v137, -v184
	v_fma_f32 v137, v5, v138, -v185
	v_fmac_f32_e32 v177, v165, v165
	v_fmac_f32_e32 v176, v137, v137
	s_waitcnt lgkmcnt(5)
	v_fma_f32 v139, v6, v139, -v186
	v_fma_f32 v138, v7, v141, -v187
	v_fmac_f32_e32 v175, v139, v139
	v_fmac_f32_e32 v171, v138, v138
	v_mov_b32_e32 v7, v1
	s_waitcnt lgkmcnt(4)
	v_fma_f32 v141, v8, v140, -v188
	v_fma_f32 v140, v9, v142, -v189
	v_fmac_f32_e32 v172, v141, v141
	v_fmac_f32_e32 v168, v140, v140
	s_waitcnt lgkmcnt(3)
	v_fma_f32 v144, v10, v144, -v190
	v_fma_f32 v142, v11, v146, -v191
	v_fmac_f32_e32 v166, v144, v144
	v_fmac_f32_e32 v161, v142, v142
	s_waitcnt lgkmcnt(2)
	v_fma_f32 v146, v12, v143, -v182
	v_fma_f32 v143, v13, v145, -v183
	v_fmac_f32_e32 v154, v146, v146
	v_fmac_f32_e32 v147, v143, v143
	s_waitcnt lgkmcnt(1)
	v_fma_f32 v167, v14, v167, -v192
	v_fma_f32 v145, v15, v169, -v193
	v_fmac_f32_e32 v149, v167, v167
	v_fmac_f32_e32 v148, v145, v145
	s_waitcnt lgkmcnt(0)
	v_fma_f32 v170, v16, v170, -v196
	v_fma_f32 v169, v17, v173, -v197
	v_fmac_f32_e32 v158, v170, v170
	v_fmac_f32_e32 v156, v169, v169
	ds_swizzle_b32 v196, v179 offset:swizzle(SWAP,1)
	ds_swizzle_b32 v197, v178 offset:swizzle(SWAP,1)
	ds_swizzle_b32 v198, v177 offset:swizzle(SWAP,1)
	ds_swizzle_b32 v199, v176 offset:swizzle(SWAP,1)
	ds_swizzle_b32 v200, v175 offset:swizzle(SWAP,1)
	ds_swizzle_b32 v201, v171 offset:swizzle(SWAP,1)
	ds_swizzle_b32 v206, v172 offset:swizzle(SWAP,1)
	ds_swizzle_b32 v207, v168 offset:swizzle(SWAP,1)
	ds_swizzle_b32 v208, v166 offset:swizzle(SWAP,1)
	ds_swizzle_b32 v209, v161 offset:swizzle(SWAP,1)
	ds_swizzle_b32 v210, v154 offset:swizzle(SWAP,1)
	s_waitcnt lgkmcnt(10)
	v_add_f32_e32 v180, v179, v196
	s_waitcnt lgkmcnt(9)
	v_add_f32_e32 v181, v178, v197
	s_waitcnt lgkmcnt(8)
	v_add_f32_e32 v182, v177, v198
	s_waitcnt lgkmcnt(7)
	v_add_f32_e32 v183, v176, v199
	s_waitcnt lgkmcnt(6)
	v_add_f32_e32 v184, v175, v200
	s_waitcnt lgkmcnt(5)
	v_add_f32_e32 v185, v171, v201
	ds_swizzle_b32 v211, v147 offset:swizzle(SWAP,1)
	ds_swizzle_b32 v212, v149 offset:swizzle(SWAP,1)
	ds_swizzle_b32 v213, v148 offset:swizzle(SWAP,1)
	ds_swizzle_b32 v214, v158 offset:swizzle(SWAP,1)
	ds_swizzle_b32 v215, v156 offset:swizzle(SWAP,1)
	s_waitcnt lgkmcnt(9)
	v_add_f32_e32 v186, v172, v206
	s_waitcnt lgkmcnt(8)
	v_add_f32_e32 v187, v168, v207
	s_waitcnt lgkmcnt(7)
	v_add_f32_e32 v188, v166, v208
	s_waitcnt lgkmcnt(6)
	v_add_f32_e32 v189, v161, v209
	s_waitcnt lgkmcnt(5)
	v_add_f32_e32 v190, v154, v210
	ds_swizzle_b32 v196, v180 offset:swizzle(SWAP,2)
	ds_swizzle_b32 v197, v181 offset:swizzle(SWAP,2)
	ds_swizzle_b32 v198, v182 offset:swizzle(SWAP,2)
	ds_swizzle_b32 v199, v183 offset:swizzle(SWAP,2)
	ds_swizzle_b32 v200, v184 offset:swizzle(SWAP,2)
	ds_swizzle_b32 v201, v185 offset:swizzle(SWAP,2)
	s_waitcnt lgkmcnt(10)
	v_add_f32_e32 v191, v147, v211
	s_waitcnt lgkmcnt(9)
	v_add_f32_e32 v192, v149, v212
	s_waitcnt lgkmcnt(8)
	v_add_f32_e32 v193, v148, v213
	s_waitcnt lgkmcnt(7)
	v_add_f32_e32 v194, v158, v214
	s_waitcnt lgkmcnt(6)
	v_add_f32_e32 v195, v156, v215
	ds_swizzle_b32 v206, v186 offset:swizzle(SWAP,2)
	ds_swizzle_b32 v207, v187 offset:swizzle(SWAP,2)
	ds_swizzle_b32 v208, v188 offset:swizzle(SWAP,2)
	ds_swizzle_b32 v209, v189 offset:swizzle(SWAP,2)
	ds_swizzle_b32 v210, v190 offset:swizzle(SWAP,2)
	s_waitcnt lgkmcnt(10)
	v_add_f32_e32 v180, v180, v196
	s_waitcnt lgkmcnt(9)
	v_add_f32_e32 v181, v181, v197
	s_waitcnt lgkmcnt(8)
	v_add_f32_e32 v182, v182, v198
	s_waitcnt lgkmcnt(7)
	v_add_f32_e32 v183, v183, v199
	s_waitcnt lgkmcnt(6)
	v_add_f32_e32 v184, v184, v200
	s_waitcnt lgkmcnt(5)
	v_add_f32_e32 v185, v185, v201
	ds_swizzle_b32 v211, v191 offset:swizzle(SWAP,2)
	ds_swizzle_b32 v212, v192 offset:swizzle(SWAP,2)
	ds_swizzle_b32 v213, v193 offset:swizzle(SWAP,2)
	ds_swizzle_b32 v214, v194 offset:swizzle(SWAP,2)
	ds_swizzle_b32 v215, v195 offset:swizzle(SWAP,2)
	s_waitcnt lgkmcnt(9)
	v_add_f32_e32 v186, v186, v206
	s_waitcnt lgkmcnt(8)
	v_add_f32_e32 v187, v187, v207
	s_waitcnt lgkmcnt(7)
	v_add_f32_e32 v188, v188, v208
	s_waitcnt lgkmcnt(6)
	v_add_f32_e32 v189, v189, v209
	s_waitcnt lgkmcnt(5)
	v_add_f32_e32 v190, v190, v210
	ds_swizzle_b32 v196, v180 offset:swizzle(SWAP,4)
	ds_swizzle_b32 v197, v181 offset:swizzle(SWAP,4)
	ds_swizzle_b32 v198, v182 offset:swizzle(SWAP,4)
	ds_swizzle_b32 v199, v183 offset:swizzle(SWAP,4)
	ds_swizzle_b32 v200, v184 offset:swizzle(SWAP,4)
	ds_swizzle_b32 v201, v185 offset:swizzle(SWAP,4)
	s_waitcnt lgkmcnt(10)
; template <bool FIXED>
; __device__ __forceinline__ void df_unit(LAS char* lds, bf16_t* QKV, const float* gsub, float lam, float post, int b, int h, int qb, int wave0, float mfix2) {
;     ...
;         for (int r = 0; r < 16; ++r) { float s = ssq[r]; s = xsum<1>(s); s = xsum<2>(s); s = xsum<4>(s); s = xsum<8>(s); s = xsum<16>(s);
	v_add_f32_e32 v191, v191, v211
	s_waitcnt lgkmcnt(9)
	v_add_f32_e32 v192, v192, v212
	s_waitcnt lgkmcnt(8)
	v_add_f32_e32 v193, v193, v213
	s_waitcnt lgkmcnt(7)
	v_add_f32_e32 v194, v194, v214
	s_waitcnt lgkmcnt(6)
	v_add_f32_e32 v195, v195, v215
	ds_swizzle_b32 v206, v186 offset:swizzle(SWAP,4)
	ds_swizzle_b32 v207, v187 offset:swizzle(SWAP,4)
	ds_swizzle_b32 v208, v188 offset:swizzle(SWAP,4)
	ds_swizzle_b32 v209, v189 offset:swizzle(SWAP,4)
	ds_swizzle_b32 v210, v190 offset:swizzle(SWAP,4)
	s_waitcnt lgkmcnt(10)
	v_add_f32_e32 v180, v180, v196
	s_waitcnt lgkmcnt(9)
	v_add_f32_e32 v181, v181, v197
	s_waitcnt lgkmcnt(8)
	v_add_f32_e32 v182, v182, v198
	s_waitcnt lgkmcnt(7)
	v_add_f32_e32 v183, v183, v199
	s_waitcnt lgkmcnt(6)
	v_add_f32_e32 v184, v184, v200
	s_waitcnt lgkmcnt(5)
	v_add_f32_e32 v185, v185, v201
	ds_swizzle_b32 v211, v191 offset:swizzle(SWAP,4)
	ds_swizzle_b32 v212, v192 offset:swizzle(SWAP,4)
	ds_swizzle_b32 v213, v193 offset:swizzle(SWAP,4)
	ds_swizzle_b32 v214, v194 offset:swizzle(SWAP,4)
	ds_swizzle_b32 v215, v195 offset:swizzle(SWAP,4)
	s_waitcnt lgkmcnt(9)
	v_add_f32_e32 v186, v186, v206
	s_waitcnt lgkmcnt(8)
	v_add_f32_e32 v187, v187, v207
	s_waitcnt lgkmcnt(7)
	v_add_f32_e32 v188, v188, v208
	s_waitcnt lgkmcnt(6)
	v_add_f32_e32 v189, v189, v209
	s_waitcnt lgkmcnt(5)
	v_add_f32_e32 v190, v190, v210
	ds_swizzle_b32 v196, v180 offset:swizzle(SWAP,8)
	ds_swizzle_b32 v197, v181 offset:swizzle(SWAP,8)
	ds_swizzle_b32 v198, v182 offset:swizzle(SWAP,8)
	ds_swizzle_b32 v199, v183 offset:swizzle(SWAP,8)
	ds_swizzle_b32 v200, v184 offset:swizzle(SWAP,8)
	ds_swizzle_b32 v201, v185 offset:swizzle(SWAP,8)
	s_waitcnt lgkmcnt(10)
	v_add_f32_e32 v191, v191, v211
	s_waitcnt lgkmcnt(9)
	v_add_f32_e32 v192, v192, v212
	s_waitcnt lgkmcnt(8)
	v_add_f32_e32 v193, v193, v213
	s_waitcnt lgkmcnt(7)
	v_add_f32_e32 v194, v194, v214
	s_waitcnt lgkmcnt(6)
	v_add_f32_e32 v195, v195, v215
	ds_swizzle_b32 v206, v186 offset:swizzle(SWAP,8)
	ds_swizzle_b32 v207, v187 offset:swizzle(SWAP,8)
	ds_swizzle_b32 v208, v188 offset:swizzle(SWAP,8)
	ds_swizzle_b32 v209, v189 offset:swizzle(SWAP,8)
	ds_swizzle_b32 v210, v190 offset:swizzle(SWAP,8)
	s_waitcnt lgkmcnt(10)
	v_add_f32_e32 v180, v180, v196
	s_waitcnt lgkmcnt(9)
	v_add_f32_e32 v181, v181, v197
	s_waitcnt lgkmcnt(8)
	v_add_f32_e32 v182, v182, v198
	s_waitcnt lgkmcnt(7)
	v_add_f32_e32 v183, v183, v199
	s_waitcnt lgkmcnt(6)
	v_add_f32_e32 v184, v184, v200
	s_waitcnt lgkmcnt(5)
	v_add_f32_e32 v185, v185, v201
	ds_swizzle_b32 v211, v191 offset:swizzle(SWAP,8)
	ds_swizzle_b32 v212, v192 offset:swizzle(SWAP,8)
	ds_swizzle_b32 v213, v193 offset:swizzle(SWAP,8)
	ds_swizzle_b32 v214, v194 offset:swizzle(SWAP,8)
	ds_swizzle_b32 v215, v195 offset:swizzle(SWAP,8)
	s_waitcnt lgkmcnt(9)
	v_add_f32_e32 v186, v186, v206
	s_waitcnt lgkmcnt(8)
	v_add_f32_e32 v187, v187, v207
	s_waitcnt lgkmcnt(7)
	v_add_f32_e32 v188, v188, v208
	s_waitcnt lgkmcnt(6)
	v_add_f32_e32 v189, v189, v209
	s_waitcnt lgkmcnt(5)
	v_add_f32_e32 v190, v190, v210
	ds_swizzle_b32 v196, v180 offset:swizzle(SWAP,16)
	ds_swizzle_b32 v197, v181 offset:swizzle(SWAP,16)
	ds_swizzle_b32 v198, v182 offset:swizzle(SWAP,16)
	ds_swizzle_b32 v199, v183 offset:swizzle(SWAP,16)
	ds_swizzle_b32 v200, v184 offset:swizzle(SWAP,16)
	ds_swizzle_b32 v201, v185 offset:swizzle(SWAP,16)
	s_waitcnt lgkmcnt(10)
	v_add_f32_e32 v191, v191, v211
	s_waitcnt lgkmcnt(9)
	v_add_f32_e32 v192, v192, v212
	s_waitcnt lgkmcnt(8)
	v_add_f32_e32 v193, v193, v213
	s_waitcnt lgkmcnt(7)
	v_add_f32_e32 v194, v194, v214
	s_waitcnt lgkmcnt(6)
	v_add_f32_e32 v195, v195, v215
	ds_swizzle_b32 v206, v186 offset:swizzle(SWAP,16)
	ds_swizzle_b32 v207, v187 offset:swizzle(SWAP,16)
	ds_swizzle_b32 v208, v188 offset:swizzle(SWAP,16)
	ds_swizzle_b32 v209, v189 offset:swizzle(SWAP,16)
	ds_swizzle_b32 v210, v190 offset:swizzle(SWAP,16)
	s_waitcnt lgkmcnt(10)
	v_add_f32_e32 v180, v180, v196
	s_waitcnt lgkmcnt(9)
	v_add_f32_e32 v181, v181, v197
	s_waitcnt lgkmcnt(8)
	v_add_f32_e32 v182, v182, v198
	s_waitcnt lgkmcnt(7)
	v_add_f32_e32 v183, v183, v199
	s_waitcnt lgkmcnt(6)
	v_add_f32_e32 v184, v184, v200
	s_waitcnt lgkmcnt(5)
	v_add_f32_e32 v185, v185, v201
	ds_swizzle_b32 v211, v191 offset:swizzle(SWAP,16)
	ds_swizzle_b32 v212, v192 offset:swizzle(SWAP,16)
	ds_swizzle_b32 v213, v193 offset:swizzle(SWAP,16)
	ds_swizzle_b32 v214, v194 offset:swizzle(SWAP,16)
	ds_swizzle_b32 v215, v195 offset:swizzle(SWAP,16)
	s_waitcnt lgkmcnt(9)
	v_add_f32_e32 v186, v186, v206
	s_waitcnt lgkmcnt(8)
	v_add_f32_e32 v187, v187, v207
	s_waitcnt lgkmcnt(7)
	v_add_f32_e32 v188, v188, v208
	s_waitcnt lgkmcnt(6)
	v_add_f32_e32 v189, v189, v209
	s_waitcnt lgkmcnt(5)
	v_add_f32_e32 v190, v190, v210
	s_waitcnt lgkmcnt(4)
	v_add_f32_e32 v191, v191, v211
	s_waitcnt lgkmcnt(3)
	v_add_f32_e32 v192, v192, v212
	s_waitcnt lgkmcnt(2)
	v_add_f32_e32 v193, v193, v213
	s_waitcnt lgkmcnt(1)
	v_add_f32_e32 v194, v194, v214
	s_waitcnt lgkmcnt(0)
; __device__ __forceinline__ int crow(int r, int hi) { return (r & 3) + 8 * (r >> 2) + 4 * hi; }
; __device__ __forceinline__ unsigned cvtpk(float lo, float hi) { unsigned r; asm volatile("v_cvt_pk_bf16_f32 %0, %1, %2" : "=v"(r) : "v"(lo), "v"(hi)); return r; }
; template <bool FIXED>
; __device__ __forceinline__ void df_unit(LAS char* lds, bf16_t* QKV, const float* gsub, float lam, float post, int b, int h, int qb, int wave0, float mfix2) {
;     ...
;         for (int r = 0; r < 16; ++r) { float s = ssq[r]; s = xsum<1>(s); s = xsum<2>(s); s = xsum<4>(s); s = xsum<8>(s); s = xsum<16>(s);
;             ssq[r] = post * __builtin_amdgcn_rsqf(s * (1.0f / 256.0f) + EPS); }
; #pragma unroll
;         for (int d = 0; d < 8; ++d) { const float g = gsub[d * 32 + r32];
; #pragma unroll
;             for (int r = 0; r < 16; ++r) *(unsigned short*)(rowsq + (size_t)crow(r, hi) * PITCH + d * 32 + r32) = (unsigned short)cvtpk(o[d][r] * ssq[r] * g, 0.f); }
	v_add_f32_e32 v195, v195, v215
	v_fmamk_f32 v180, v180, 0x3b800000, v223
	v_fmamk_f32 v181, v181, 0x3b800000, v223
	v_fmamk_f32 v182, v182, 0x3b800000, v223
	v_fmamk_f32 v183, v183, 0x3b800000, v223
	v_fmamk_f32 v184, v184, 0x3b800000, v223
	v_fmamk_f32 v185, v185, 0x3b800000, v223
	v_fmamk_f32 v186, v186, 0x3b800000, v223
	v_fmamk_f32 v187, v187, 0x3b800000, v223
	v_fmamk_f32 v188, v188, 0x3b800000, v223
	v_fmamk_f32 v189, v189, 0x3b800000, v223
	v_fmamk_f32 v190, v190, 0x3b800000, v223
	v_fmamk_f32 v191, v191, 0x3b800000, v223
	v_fmamk_f32 v192, v192, 0x3b800000, v223
	v_fmamk_f32 v193, v193, 0x3b800000, v223
	v_fmamk_f32 v194, v194, 0x3b800000, v223
	v_fmamk_f32 v195, v195, 0x3b800000, v223
	v_rsq_f32_e32 v180, v180
	v_rsq_f32_e32 v181, v181
	v_rsq_f32_e32 v182, v182
	v_rsq_f32_e32 v183, v183
	v_rsq_f32_e32 v184, v184
	v_rsq_f32_e32 v185, v185
	v_rsq_f32_e32 v186, v186
	v_rsq_f32_e32 v187, v187
	v_rsq_f32_e32 v188, v188
	v_rsq_f32_e32 v189, v189
	v_rsq_f32_e32 v190, v190
	v_rsq_f32_e32 v191, v191
	v_rsq_f32_e32 v192, v192
	v_rsq_f32_e32 v193, v193
	v_rsq_f32_e32 v194, v194
	v_rsq_f32_e32 v195, v195
	v_mul_f32_e32 v173, v232, v180
	v_mul_f32_e32 v174, v232, v181
	v_mul_f32_e32 v177, v232, v182
	v_mul_f32_e32 v176, v232, v183
	v_mul_f32_e32 v175, v232, v184
	v_mul_f32_e32 v171, v232, v185
	v_mul_f32_e32 v172, v232, v186
	v_mul_f32_e32 v168, v232, v187
	v_mul_f32_e32 v166, v232, v188
	v_mul_f32_e32 v161, v232, v189
	v_mul_f32_e32 v154, v232, v190
	v_mul_f32_e32 v147, v232, v191
	v_mul_f32_e32 v149, v232, v192
	v_mul_f32_e32 v148, v232, v193
	v_mul_f32_e32 v158, v232, v194
	v_mul_f32_e32 v156, v232, v195
	v_mul_f32_e32 v114, v114, v173
	v_lshlrev_b32_e32 v178, 2, v203
	global_load_dword v179, v178, s[68:69]
	v_mul_f32_e32 v98, v98, v174
	v_mul_f32_e32 v82, v82, v174
	v_mul_f32_e32 v66, v66, v174
	v_mul_f32_e32 v50, v50, v174
	v_mul_f32_e32 v34, v34, v174
	s_lshl_b32 s0, s27, 15
	v_lshlrev_b32_e32 v183, 11, v202
	v_lshl_add_u32 v180, v203, 1, v183
	v_add_u32_e32 v180, s0, v180
	v_lshl_add_u32 v181, v204, 4, s0
	v_mul_u32_u24_e32 v182, 0x3000, v202
	v_lshl_add_u32 v182, v203, 4, v182
	v_mul_f32_e32 v0, v135, v173
	s_waitcnt vmcnt(0)
	v_mul_f32_e32 v0, v0, v179
	v_cvt_pk_bf16_f32 v6, v0, v1
	ds_write_b16 v180, v6 offset:0
	v_mul_f32_e32 v6, v131, v174
	v_mul_f32_e32 v6, v6, v179
	v_cvt_pk_bf16_f32 v10, v6, v1
	ds_write_b16 v180, v10 offset:512
	v_mul_f32_e32 v8, v132, v177
	v_mul_f32_e32 v8, v8, v179
	v_cvt_pk_bf16_f32 v10, v8, v1
	ds_write_b16 v180, v10 offset:1024
	v_mul_f32_e32 v10, v117, v176
	v_mul_f32_e32 v10, v10, v179
	v_cvt_pk_bf16_f32 v12, v10, v1
	ds_write_b16 v180, v12 offset:1536
	v_mul_f32_e32 v12, v130, v175
	v_mul_f32_e32 v12, v12, v179
	v_cvt_pk_bf16_f32 v14, v12, v1
	ds_write_b16 v180, v14 offset:4096
	v_mul_f32_e32 v14, v115, v171
	v_mul_f32_e32 v14, v14, v179
	v_cvt_pk_bf16_f32 v16, v14, v1
	ds_write_b16 v180, v16 offset:4608
	v_mul_f32_e32 v16, v134, v172
	v_mul_f32_e32 v16, v16, v179
	v_cvt_pk_bf16_f32 v18, v16, v1
	ds_write_b16 v180, v18 offset:5120
	v_mul_f32_e32 v18, v119, v168
	v_mul_f32_e32 v18, v18, v179
	v_cvt_pk_bf16_f32 v22, v18, v1
	ds_write_b16 v180, v22 offset:5632
	v_mul_f32_e32 v20, v133, v166
	v_mul_f32_e32 v20, v20, v179
	v_cvt_pk_bf16_f32 v24, v20, v1
	ds_write_b16 v180, v24 offset:8192
	v_mul_f32_e32 v22, v120, v161
	v_mul_f32_e32 v22, v22, v179
	v_cvt_pk_bf16_f32 v26, v22, v1
	ds_write_b16 v180, v26 offset:8704
	v_mul_f32_e32 v24, v123, v154
	v_mul_f32_e32 v24, v24, v179
	v_cvt_pk_bf16_f32 v26, v24, v1
	ds_write_b16 v180, v26 offset:9216
	v_mul_f32_e32 v26, v118, v147
	v_mul_f32_e32 v26, v26, v179
	v_cvt_pk_bf16_f32 v28, v26, v1
	ds_write_b16 v180, v28 offset:9728
	v_mul_f32_e32 v28, v122, v149
	v_mul_f32_e32 v28, v28, v179
	v_cvt_pk_bf16_f32 v30, v28, v1
	ds_write_b16 v180, v30 offset:12288
	v_mul_f32_e32 v30, v116, v148
	v_mul_f32_e32 v30, v30, v179
	v_cvt_pk_bf16_f32 v32, v30, v1
	ds_write_b16 v180, v32 offset:12800
	v_mul_f32_e32 v32, v124, v158
	v_mul_f32_e32 v32, v179, v32
	v_cvt_pk_bf16_f32 v115, v32, v1
	ds_write_b16 v180, v115 offset:13312
	v_mul_f32_e32 v115, v121, v156
	v_mul_f32_e32 v115, v179, v115
	v_cvt_pk_bf16_f32 v115, v115, v1
	global_load_dword v118, v178, s[68:69] offset:128
	ds_write_b16 v180, v115 offset:13824
	s_waitcnt vmcnt(0)
	v_mul_f32_e32 v114, v114, v118
	v_cvt_pk_bf16_f32 v114, v114, v1
	v_mul_f32_e32 v98, v98, v118
	ds_write_b16 v180, v114 offset:64
	v_cvt_pk_bf16_f32 v98, v98, v1
	ds_write_b16 v180, v98 offset:576
	v_mul_f32_e32 v98, v100, v177
	v_mul_f32_e32 v98, v98, v118
	v_cvt_pk_bf16_f32 v98, v98, v1
	ds_write_b16 v180, v98 offset:1088
	v_mul_f32_e32 v98, v99, v176
	v_mul_f32_e32 v98, v98, v118
	v_cvt_pk_bf16_f32 v98, v98, v1
	ds_write_b16 v180, v98 offset:1600
	v_mul_f32_e32 v98, v102, v175
	v_mul_f32_e32 v98, v98, v118
	v_cvt_pk_bf16_f32 v98, v98, v1
	ds_write_b16 v180, v98 offset:4160
	v_mul_f32_e32 v98, v101, v171
	v_mul_f32_e32 v98, v98, v118
	v_cvt_pk_bf16_f32 v98, v98, v1
	ds_write_b16 v180, v98 offset:4672
	v_mul_f32_e32 v98, v104, v172
	v_mul_f32_e32 v98, v98, v118
	v_cvt_pk_bf16_f32 v98, v98, v1
	ds_write_b16 v180, v98 offset:5184
	v_mul_f32_e32 v98, v103, v168
	v_mul_f32_e32 v98, v98, v118
	v_cvt_pk_bf16_f32 v100, v98, v1
	ds_write_b16 v180, v100 offset:5696
	v_mul_f32_e32 v98, v106, v166
	v_mul_f32_e32 v98, v98, v118
	v_cvt_pk_bf16_f32 v100, v98, v1
	ds_write_b16 v180, v100 offset:8256
	v_mul_f32_e32 v98, v105, v161
	v_mul_f32_e32 v98, v98, v118
	v_cvt_pk_bf16_f32 v100, v98, v1
	ds_write_b16 v180, v100 offset:8768
	v_mul_f32_e32 v98, v108, v154
	v_mul_f32_e32 v98, v98, v118
	v_cvt_pk_bf16_f32 v98, v98, v1
	ds_write_b16 v180, v98 offset:9280
	v_mul_f32_e32 v98, v107, v147
	v_mul_f32_e32 v98, v98, v118
	v_cvt_pk_bf16_f32 v98, v98, v1
	ds_write_b16 v180, v98 offset:9792
	v_mul_f32_e32 v98, v110, v149
	v_mul_f32_e32 v98, v98, v118
	v_cvt_pk_bf16_f32 v98, v98, v1
	ds_write_b16 v180, v98 offset:12352
	v_mul_f32_e32 v98, v109, v148
	v_mul_f32_e32 v98, v98, v118
	v_cvt_pk_bf16_f32 v98, v98, v1
	ds_write_b16 v180, v98 offset:12864
	v_mul_f32_e32 v98, v112, v158
	v_mul_f32_e32 v98, v98, v118
	v_cvt_pk_bf16_f32 v98, v98, v1
	ds_write_b16 v180, v98 offset:13376
	v_mul_f32_e32 v98, v113, v156
	v_mul_f32_e32 v98, v98, v118
	v_cvt_pk_bf16_f32 v100, v98, v1
	global_load_dword v102, v178, s[68:69] offset:256
	ds_write_b16 v180, v100 offset:13888
	v_mul_f32_e32 v100, v111, v173
	s_waitcnt vmcnt(0)
; __device__ __forceinline__ int crow(int r, int hi) { return (r & 3) + 8 * (r >> 2) + 4 * hi; }
; __device__ __forceinline__ unsigned cvtpk(float lo, float hi) { unsigned r; asm volatile("v_cvt_pk_bf16_f32 %0, %1, %2" : "=v"(r) : "v"(lo), "v"(hi)); return r; }
; template <bool FIXED>
; __device__ __forceinline__ void df_unit(LAS char* lds, bf16_t* QKV, const float* gsub, float lam, float post, int b, int h, int qb, int wave0, float mfix2) {
;     ...
;         for (int d = 0; d < 8; ++d) { const float g = gsub[d * 32 + r32];
; #pragma unroll
;             for (int r = 0; r < 16; ++r) *(unsigned short*)(rowsq + (size_t)crow(r, hi) * PITCH + d * 32 + r32) = (unsigned short)cvtpk(o[d][r] * ssq[r] * g, 0.f); }
	v_mul_f32_e32 v100, v100, v102
	v_cvt_pk_bf16_f32 v100, v100, v1
	v_mul_f32_e32 v82, v82, v102
	ds_write_b16 v180, v100 offset:128
	v_cvt_pk_bf16_f32 v82, v82, v1
	ds_write_b16 v180, v82 offset:640
	v_mul_f32_e32 v82, v84, v177
	v_mul_f32_e32 v82, v82, v102
	v_cvt_pk_bf16_f32 v82, v82, v1
	ds_write_b16 v180, v82 offset:1152
	v_mul_f32_e32 v82, v83, v176
	v_mul_f32_e32 v82, v82, v102
	v_cvt_pk_bf16_f32 v82, v82, v1
	ds_write_b16 v180, v82 offset:1664
	v_mul_f32_e32 v82, v86, v175
	v_mul_f32_e32 v82, v82, v102
	v_cvt_pk_bf16_f32 v82, v82, v1
	ds_write_b16 v180, v82 offset:4224
	v_mul_f32_e32 v82, v85, v171
	v_mul_f32_e32 v82, v82, v102
	v_cvt_pk_bf16_f32 v82, v82, v1
	ds_write_b16 v180, v82 offset:4736
	v_mul_f32_e32 v82, v88, v172
	v_mul_f32_e32 v82, v82, v102
	v_cvt_pk_bf16_f32 v82, v82, v1
	ds_write_b16 v180, v82 offset:5248
	v_mul_f32_e32 v82, v87, v168
	v_mul_f32_e32 v82, v82, v102
	v_cvt_pk_bf16_f32 v84, v82, v1
	ds_write_b16 v180, v84 offset:5760
	v_mul_f32_e32 v82, v90, v166
	v_mul_f32_e32 v82, v82, v102
	v_cvt_pk_bf16_f32 v84, v82, v1
	ds_write_b16 v180, v84 offset:8320
	v_mul_f32_e32 v82, v89, v161
	v_mul_f32_e32 v82, v82, v102
	v_cvt_pk_bf16_f32 v84, v82, v1
	ds_write_b16 v180, v84 offset:8832
	v_mul_f32_e32 v82, v92, v154
	v_mul_f32_e32 v82, v82, v102
	v_cvt_pk_bf16_f32 v82, v82, v1
	ds_write_b16 v180, v82 offset:9344
	v_mul_f32_e32 v82, v91, v147
	v_mul_f32_e32 v82, v82, v102
	v_cvt_pk_bf16_f32 v82, v82, v1
	ds_write_b16 v180, v82 offset:9856
	v_mul_f32_e32 v82, v94, v149
	v_mul_f32_e32 v82, v82, v102
	v_cvt_pk_bf16_f32 v82, v82, v1
	ds_write_b16 v180, v82 offset:12416
	v_mul_f32_e32 v82, v93, v148
	v_mul_f32_e32 v82, v82, v102
	v_cvt_pk_bf16_f32 v82, v82, v1
	ds_write_b16 v180, v82 offset:12928
	v_mul_f32_e32 v82, v125, v158
	v_mul_f32_e32 v82, v82, v102
	v_cvt_pk_bf16_f32 v82, v82, v1
	ds_write_b16 v180, v82 offset:13440
	v_mul_f32_e32 v82, v96, v156
	v_mul_f32_e32 v82, v82, v102
	v_cvt_pk_bf16_f32 v84, v82, v1
	global_load_dword v86, v178, s[68:69] offset:384
	ds_write_b16 v180, v84 offset:13952
	v_mul_f32_e32 v84, v95, v173
	s_waitcnt vmcnt(0)
	v_mul_f32_e32 v84, v84, v86
	v_cvt_pk_bf16_f32 v84, v84, v1
	v_mul_f32_e32 v66, v66, v86
	ds_write_b16 v180, v84 offset:192
	v_cvt_pk_bf16_f32 v66, v66, v1
	ds_write_b16 v180, v66 offset:704
	v_mul_f32_e32 v66, v68, v177
	v_mul_f32_e32 v66, v66, v86
	v_cvt_pk_bf16_f32 v66, v66, v1
	ds_write_b16 v180, v66 offset:1216
	v_mul_f32_e32 v66, v67, v176
	v_mul_f32_e32 v66, v66, v86
	v_cvt_pk_bf16_f32 v66, v66, v1
	ds_write_b16 v180, v66 offset:1728
	v_mul_f32_e32 v66, v70, v175
	v_mul_f32_e32 v66, v66, v86
	v_cvt_pk_bf16_f32 v66, v66, v1
	ds_write_b16 v180, v66 offset:4288
	v_mul_f32_e32 v66, v69, v171
	v_mul_f32_e32 v66, v66, v86
	v_cvt_pk_bf16_f32 v66, v66, v1
	ds_write_b16 v180, v66 offset:4800
	v_mul_f32_e32 v66, v72, v172
	v_mul_f32_e32 v66, v66, v86
	v_cvt_pk_bf16_f32 v66, v66, v1
	ds_write_b16 v180, v66 offset:5312
	v_mul_f32_e32 v66, v71, v168
	v_mul_f32_e32 v66, v66, v86
	v_cvt_pk_bf16_f32 v68, v66, v1
	ds_write_b16 v180, v68 offset:5824
	v_mul_f32_e32 v66, v74, v166
	v_mul_f32_e32 v66, v66, v86
	v_cvt_pk_bf16_f32 v68, v66, v1
	ds_write_b16 v180, v68 offset:8384
	v_mul_f32_e32 v66, v73, v161
	v_mul_f32_e32 v66, v66, v86
	v_cvt_pk_bf16_f32 v68, v66, v1
	ds_write_b16 v180, v68 offset:8896
	v_mul_f32_e32 v66, v76, v154
	v_mul_f32_e32 v66, v66, v86
	v_cvt_pk_bf16_f32 v66, v66, v1
	ds_write_b16 v180, v66 offset:9408
	v_mul_f32_e32 v66, v75, v147
	v_mul_f32_e32 v66, v66, v86
	v_cvt_pk_bf16_f32 v66, v66, v1
	ds_write_b16 v180, v66 offset:9920
	v_mul_f32_e32 v66, v78, v149
	v_mul_f32_e32 v66, v66, v86
	v_cvt_pk_bf16_f32 v66, v66, v1
	ds_write_b16 v180, v66 offset:12480
	v_mul_f32_e32 v66, v77, v148
	v_mul_f32_e32 v66, v66, v86
	v_cvt_pk_bf16_f32 v66, v66, v1
	ds_write_b16 v180, v66 offset:12992
	v_mul_f32_e32 v66, v97, v158
	v_mul_f32_e32 v66, v66, v86
	v_cvt_pk_bf16_f32 v66, v66, v1
	ds_write_b16 v180, v66 offset:13504
	v_mul_f32_e32 v66, v80, v156
	v_mul_f32_e32 v66, v66, v86
	v_cvt_pk_bf16_f32 v68, v66, v1
	global_load_dword v70, v178, s[68:69] offset:512
	ds_write_b16 v180, v68 offset:14016
	v_mul_f32_e32 v68, v79, v173
	s_waitcnt vmcnt(0)
	v_mul_f32_e32 v68, v68, v70
	v_cvt_pk_bf16_f32 v68, v68, v1
	v_mul_f32_e32 v50, v50, v70
	ds_write_b16 v180, v68 offset:256
	v_cvt_pk_bf16_f32 v50, v50, v1
	ds_write_b16 v180, v50 offset:768
	v_mul_f32_e32 v50, v52, v177
	v_mul_f32_e32 v50, v50, v70
	v_cvt_pk_bf16_f32 v50, v50, v1
	ds_write_b16 v180, v50 offset:1280
	v_mul_f32_e32 v50, v51, v176
	v_mul_f32_e32 v50, v50, v70
	v_cvt_pk_bf16_f32 v50, v50, v1
	ds_write_b16 v180, v50 offset:1792
	v_mul_f32_e32 v50, v54, v175
	v_mul_f32_e32 v50, v50, v70
	v_cvt_pk_bf16_f32 v50, v50, v1
	ds_write_b16 v180, v50 offset:4352
	v_mul_f32_e32 v50, v53, v171
	v_mul_f32_e32 v50, v50, v70
	v_cvt_pk_bf16_f32 v50, v50, v1
	ds_write_b16 v180, v50 offset:4864
	v_mul_f32_e32 v50, v56, v172
	v_mul_f32_e32 v50, v50, v70
	v_cvt_pk_bf16_f32 v50, v50, v1
	ds_write_b16 v180, v50 offset:5376
	v_mul_f32_e32 v50, v55, v168
	v_mul_f32_e32 v50, v50, v70
	v_cvt_pk_bf16_f32 v52, v50, v1
	ds_write_b16 v180, v52 offset:5888
	v_mul_f32_e32 v50, v58, v166
	v_mul_f32_e32 v50, v50, v70
	v_cvt_pk_bf16_f32 v52, v50, v1
	ds_write_b16 v180, v52 offset:8448
	v_mul_f32_e32 v50, v57, v161
	v_mul_f32_e32 v50, v50, v70
	v_cvt_pk_bf16_f32 v52, v50, v1
	ds_write_b16 v180, v52 offset:8960
	v_mul_f32_e32 v50, v60, v154
	v_mul_f32_e32 v50, v50, v70
	v_cvt_pk_bf16_f32 v50, v50, v1
	ds_write_b16 v180, v50 offset:9472
	v_mul_f32_e32 v50, v59, v147
	v_mul_f32_e32 v50, v50, v70
	v_cvt_pk_bf16_f32 v50, v50, v1
	ds_write_b16 v180, v50 offset:9984
	v_mul_f32_e32 v50, v62, v149
	v_mul_f32_e32 v50, v50, v70
	v_cvt_pk_bf16_f32 v50, v50, v1
	ds_write_b16 v180, v50 offset:12544
	v_mul_f32_e32 v50, v61, v148
	v_mul_f32_e32 v50, v50, v70
	v_cvt_pk_bf16_f32 v50, v50, v1
	ds_write_b16 v180, v50 offset:13056
	v_mul_f32_e32 v50, v81, v158
	v_mul_f32_e32 v50, v50, v70
	v_cvt_pk_bf16_f32 v50, v50, v1
	ds_write_b16 v180, v50 offset:13568
	v_mul_f32_e32 v50, v64, v156
	v_mul_f32_e32 v50, v50, v70
	v_cvt_pk_bf16_f32 v52, v50, v1
	global_load_dword v54, v178, s[68:69] offset:640
	ds_write_b16 v180, v52 offset:14080
	v_mul_f32_e32 v52, v63, v173
	s_waitcnt vmcnt(0)
; __device__ __forceinline__ int crow(int r, int hi) { return (r & 3) + 8 * (r >> 2) + 4 * hi; }
; __device__ __forceinline__ unsigned cvtpk(float lo, float hi) { unsigned r; asm volatile("v_cvt_pk_bf16_f32 %0, %1, %2" : "=v"(r) : "v"(lo), "v"(hi)); return r; }
; template <bool FIXED>
; __device__ __forceinline__ void df_unit(LAS char* lds, bf16_t* QKV, const float* gsub, float lam, float post, int b, int h, int qb, int wave0, float mfix2) {
;     ...
;         for (int d = 0; d < 8; ++d) { const float g = gsub[d * 32 + r32];
; #pragma unroll
;             for (int r = 0; r < 16; ++r) *(unsigned short*)(rowsq + (size_t)crow(r, hi) * PITCH + d * 32 + r32) = (unsigned short)cvtpk(o[d][r] * ssq[r] * g, 0.f); }
	v_mul_f32_e32 v52, v52, v54
	v_cvt_pk_bf16_f32 v52, v52, v1
	v_mul_f32_e32 v34, v34, v54
	ds_write_b16 v180, v52 offset:320
	v_cvt_pk_bf16_f32 v34, v34, v1
	ds_write_b16 v180, v34 offset:832
	v_mul_f32_e32 v34, v36, v177
	v_mul_f32_e32 v34, v34, v54
	v_cvt_pk_bf16_f32 v34, v34, v1
	ds_write_b16 v180, v34 offset:1344
	v_mul_f32_e32 v34, v35, v176
	v_mul_f32_e32 v34, v34, v54
	v_cvt_pk_bf16_f32 v34, v34, v1
	ds_write_b16 v180, v34 offset:1856
	v_mul_f32_e32 v34, v38, v175
	v_mul_f32_e32 v34, v34, v54
	v_cvt_pk_bf16_f32 v34, v34, v1
	ds_write_b16 v180, v34 offset:4416
	v_mul_f32_e32 v34, v37, v171
	v_mul_f32_e32 v34, v34, v54
	v_cvt_pk_bf16_f32 v34, v34, v1
	ds_write_b16 v180, v34 offset:4928
	v_mul_f32_e32 v34, v40, v172
	v_mul_f32_e32 v34, v34, v54
	v_cvt_pk_bf16_f32 v34, v34, v1
	ds_write_b16 v180, v34 offset:5440
	v_mul_f32_e32 v34, v39, v168
	v_mul_f32_e32 v34, v34, v54
	v_cvt_pk_bf16_f32 v36, v34, v1
	ds_write_b16 v180, v36 offset:5952
	v_mul_f32_e32 v34, v42, v166
	v_mul_f32_e32 v34, v34, v54
	v_cvt_pk_bf16_f32 v36, v34, v1
	ds_write_b16 v180, v36 offset:8512
	v_mul_f32_e32 v34, v41, v161
	v_mul_f32_e32 v34, v34, v54
	v_cvt_pk_bf16_f32 v36, v34, v1
	ds_write_b16 v180, v36 offset:9024
	v_mul_f32_e32 v34, v44, v154
	v_mul_f32_e32 v34, v34, v54
	v_cvt_pk_bf16_f32 v34, v34, v1
	ds_write_b16 v180, v34 offset:9536
	v_mul_f32_e32 v34, v43, v147
	v_mul_f32_e32 v34, v34, v54
	v_cvt_pk_bf16_f32 v34, v34, v1
	ds_write_b16 v180, v34 offset:10048
	v_mul_f32_e32 v34, v46, v149
	v_mul_f32_e32 v34, v34, v54
	v_cvt_pk_bf16_f32 v34, v34, v1
	ds_write_b16 v180, v34 offset:12608
	v_mul_f32_e32 v34, v45, v148
	v_mul_f32_e32 v34, v34, v54
	v_cvt_pk_bf16_f32 v34, v34, v1
	ds_write_b16 v180, v34 offset:13120
	v_mul_f32_e32 v34, v65, v158
	v_mul_f32_e32 v34, v34, v54
	v_cvt_pk_bf16_f32 v34, v34, v1
	ds_write_b16 v180, v34 offset:13632
	v_mul_f32_e32 v34, v49, v156
	v_mul_f32_e32 v34, v34, v54
	v_cvt_pk_bf16_f32 v36, v34, v1
	global_load_dword v38, v178, s[68:69] offset:768
	ds_write_b16 v180, v36 offset:14144
	v_mul_f32_e32 v36, v48, v173
	s_waitcnt vmcnt(0)
	v_mul_f32_e32 v36, v36, v38
	v_cvt_pk_bf16_f32 v36, v36, v1
	ds_write_b16 v180, v36 offset:384
	v_mul_f32_e32 v36, v47, v174
	v_mul_f32_e32 v36, v36, v38
	v_cvt_pk_bf16_f32 v39, v36, v1
	ds_write_b16 v180, v39 offset:896
	v_mul_f32_e32 v36, v127, v177
	v_mul_f32_e32 v36, v36, v38
	v_cvt_pk_bf16_f32 v36, v36, v1
	ds_write_b16 v180, v36 offset:1408
	v_mul_f32_e32 v36, v126, v176
	v_mul_f32_e32 v36, v36, v38
	v_cvt_pk_bf16_f32 v36, v36, v1
	ds_write_b16 v180, v36 offset:1920
	v_mul_f32_e32 v36, v129, v175
	v_mul_f32_e32 v36, v36, v38
	v_cvt_pk_bf16_f32 v36, v36, v1
	ds_write_b16 v180, v36 offset:4480
	v_mul_f32_e32 v36, v128, v171
	v_mul_f32_e32 v36, v36, v38
	v_cvt_pk_bf16_f32 v36, v36, v1
	ds_write_b16 v180, v36 offset:4992
	v_mul_f32_e32 v36, v151, v172
	v_mul_f32_e32 v36, v36, v38
	v_cvt_pk_bf16_f32 v36, v36, v1
	ds_write_b16 v180, v36 offset:5504
	v_mul_f32_e32 v36, v150, v168
	v_mul_f32_e32 v36, v36, v38
	v_cvt_pk_bf16_f32 v39, v36, v1
	ds_write_b16 v180, v39 offset:6016
	v_mul_f32_e32 v36, v153, v166
	v_mul_f32_e32 v36, v36, v38
	v_cvt_pk_bf16_f32 v39, v36, v1
	ds_write_b16 v180, v39 offset:8576
	v_mul_f32_e32 v36, v152, v161
	v_mul_f32_e32 v36, v36, v38
	v_cvt_pk_bf16_f32 v39, v36, v1
	ds_write_b16 v180, v39 offset:9088
	v_mul_f32_e32 v36, v157, v154
	v_mul_f32_e32 v36, v36, v38
	v_cvt_pk_bf16_f32 v36, v36, v1
	ds_write_b16 v180, v36 offset:9600
	v_mul_f32_e32 v36, v155, v147
	v_mul_f32_e32 v36, v36, v38
	v_cvt_pk_bf16_f32 v36, v36, v1
	ds_write_b16 v180, v36 offset:10112
	v_mul_f32_e32 v36, v160, v149
	v_mul_f32_e32 v36, v36, v38
	v_cvt_pk_bf16_f32 v36, v36, v1
	ds_write_b16 v180, v36 offset:12672
	v_mul_f32_e32 v36, v159, v148
	v_mul_f32_e32 v36, v36, v38
	v_cvt_pk_bf16_f32 v36, v36, v1
	ds_write_b16 v180, v36 offset:13184
	v_mul_f32_e32 v36, v164, v158
	v_mul_f32_e32 v36, v36, v38
	v_cvt_pk_bf16_f32 v36, v36, v1
	ds_write_b16 v180, v36 offset:13696
	v_mul_f32_e32 v36, v163, v156
	v_mul_f32_e32 v36, v36, v38
	v_cvt_pk_bf16_f32 v36, v36, v1
	ds_write_b16 v180, v36 offset:14208
	global_load_dword v34, v178, s[68:69] offset:896
	v_mul_f32_e32 v35, v162, v173
	s_waitcnt vmcnt(0)
; __device__ __forceinline__ int crow(int r, int hi) { return (r & 3) + 8 * (r >> 2) + 4 * hi; }
; __device__ __forceinline__ unsigned cvtpk(float lo, float hi) { unsigned r; asm volatile("v_cvt_pk_bf16_f32 %0, %1, %2" : "=v"(r) : "v"(lo), "v"(hi)); return r; }
; template <bool FIXED>
; __device__ __forceinline__ void df_unit(LAS char* lds, bf16_t* QKV, const float* gsub, float lam, float post, int b, int h, int qb, int wave0, float mfix2) {
;     ...
;         for (int d = 0; d < 8; ++d) { const float g = gsub[d * 32 + r32];
; #pragma unroll
;             for (int r = 0; r < 16; ++r) *(unsigned short*)(rowsq + (size_t)crow(r, hi) * PITCH + d * 32 + r32) = (unsigned short)cvtpk(o[d][r] * ssq[r] * g, 0.f); }
	v_mul_f32_e32 v35, v35, v34
	v_cvt_pk_bf16_f32 v35, v35, v1
	ds_write_b16 v180, v35 offset:448
	v_mul_f32_e32 v4, v136, v174
	v_mul_f32_e32 v4, v4, v34
	v_cvt_pk_bf16_f32 v35, v4, v1
	ds_write_b16 v180, v35 offset:960
	v_mul_f32_e32 v4, v165, v177
	v_mul_f32_e32 v4, v4, v34
	v_cvt_pk_bf16_f32 v4, v4, v1
	ds_write_b16 v180, v4 offset:1472
	v_mul_f32_e32 v4, v137, v176
	v_mul_f32_e32 v4, v4, v34
	v_cvt_pk_bf16_f32 v4, v4, v1
	ds_write_b16 v180, v4 offset:1984
	v_mul_f32_e32 v4, v139, v175
	v_mul_f32_e32 v4, v4, v34
	v_cvt_pk_bf16_f32 v4, v4, v1
	ds_write_b16 v180, v4 offset:4544
	v_mul_f32_e32 v4, v138, v171
	v_mul_f32_e32 v4, v4, v34
	v_cvt_pk_bf16_f32 v4, v4, v1
	ds_write_b16 v180, v4 offset:5056
	v_mul_f32_e32 v4, v141, v172
	v_mul_f32_e32 v4, v4, v34
	v_cvt_pk_bf16_f32 v4, v4, v1
	ds_write_b16 v180, v4 offset:5568
	v_mul_f32_e32 v4, v140, v168
	v_mul_f32_e32 v4, v4, v34
	v_cvt_pk_bf16_f32 v6, v4, v1
	ds_write_b16 v180, v6 offset:6080
	v_mul_f32_e32 v4, v144, v166
	v_mul_f32_e32 v4, v4, v34
	v_cvt_pk_bf16_f32 v6, v4, v1
	ds_write_b16 v180, v6 offset:8640
	v_mul_f32_e32 v4, v142, v161
	v_mul_f32_e32 v4, v4, v34
	v_cvt_pk_bf16_f32 v6, v4, v1
	ds_write_b16 v180, v6 offset:9152
	v_mul_f32_e32 v4, v146, v154
	v_mul_f32_e32 v4, v4, v34
	v_cvt_pk_bf16_f32 v4, v4, v1
	ds_write_b16 v180, v4 offset:9664
	v_mul_f32_e32 v4, v143, v147
	v_mul_f32_e32 v4, v4, v34
	v_cvt_pk_bf16_f32 v4, v4, v1
	ds_write_b16 v180, v4 offset:10176
	v_mul_f32_e32 v4, v167, v149
	v_mul_f32_e32 v4, v4, v34
	v_cvt_pk_bf16_f32 v4, v4, v1
	ds_write_b16 v180, v4 offset:12736
	v_mul_f32_e32 v4, v145, v148
	v_mul_f32_e32 v4, v4, v34
	v_cvt_pk_bf16_f32 v4, v4, v1
	ds_write_b16 v180, v4 offset:13248
	v_mul_f32_e32 v4, v170, v158
	v_mul_f32_e32 v4, v4, v34
	v_cvt_pk_bf16_f32 v4, v4, v1
	ds_write_b16 v180, v4 offset:13760
	v_mul_f32_e32 v4, v169, v156
	v_mul_f32_e32 v4, v4, v34
	v_cvt_pk_bf16_f32 v4, v4, v1
	ds_write_b16 v180, v4 offset:14272
	s_waitcnt vmcnt(0) lgkmcnt(0)
	ds_read_b128 v[184:187], v181 offset:0
	ds_read_b128 v[188:191], v181 offset:1024
	ds_read_b128 v[192:195], v181 offset:2048
	ds_read_b128 v[196:199], v181 offset:3072
	ds_read_b128 v[206:209], v181 offset:4096
	s_waitcnt lgkmcnt(4)
	global_store_dwordx4 v182, v[184:187], s[8:9]
	v_add_u32_e32 v182, 0x6000, v182
	ds_read_b128 v[210:213], v181 offset:5120
	s_waitcnt lgkmcnt(4)
	global_store_dwordx4 v182, v[188:191], s[8:9]
	v_add_u32_e32 v182, 0x6000, v182
	ds_read_b128 v[234:237], v181 offset:6144
	s_waitcnt lgkmcnt(4)
	global_store_dwordx4 v182, v[192:195], s[8:9]
	v_add_u32_e32 v182, 0x6000, v182
	ds_read_b128 v[238:241], v181 offset:7168
	s_waitcnt lgkmcnt(4)
	global_store_dwordx4 v182, v[196:199], s[8:9]
	v_add_u32_e32 v182, 0x6000, v182
	ds_read_b128 v[242:245], v181 offset:8192
	s_waitcnt lgkmcnt(4)
	global_store_dwordx4 v182, v[206:209], s[8:9]
	v_add_u32_e32 v182, 0x6000, v182
	ds_read_b128 v[246:249], v181 offset:9216
	s_waitcnt lgkmcnt(4)
	global_store_dwordx4 v182, v[210:213], s[8:9]
	v_add_u32_e32 v182, 0x6000, v182
	ds_read_b128 v[184:187], v181 offset:10240
	s_waitcnt lgkmcnt(4)
	global_store_dwordx4 v182, v[234:237], s[8:9]
	v_add_u32_e32 v182, 0x6000, v182
	ds_read_b128 v[188:191], v181 offset:11264
	s_waitcnt lgkmcnt(4)
	global_store_dwordx4 v182, v[238:241], s[8:9]
	v_add_u32_e32 v182, 0x6000, v182
	ds_read_b128 v[192:195], v181 offset:12288
	s_waitcnt lgkmcnt(4)
	global_store_dwordx4 v182, v[242:245], s[8:9]
	v_add_u32_e32 v182, 0x6000, v182
	ds_read_b128 v[196:199], v181 offset:13312
	s_waitcnt lgkmcnt(4)
	global_store_dwordx4 v182, v[246:249], s[8:9]
	v_add_u32_e32 v182, 0x6000, v182
	ds_read_b128 v[206:209], v181 offset:14336
	s_waitcnt lgkmcnt(4)
	global_store_dwordx4 v182, v[184:187], s[8:9]
	v_add_u32_e32 v182, 0x6000, v182
	ds_read_b128 v[210:213], v181 offset:15360
	s_waitcnt lgkmcnt(4)
	global_store_dwordx4 v182, v[188:191], s[8:9]
	v_add_u32_e32 v182, 0x6000, v182
	s_waitcnt lgkmcnt(3)
	global_store_dwordx4 v182, v[192:195], s[8:9]
	v_add_u32_e32 v182, 0x6000, v182
	s_waitcnt lgkmcnt(2)
	global_store_dwordx4 v182, v[196:199], s[8:9]
	v_add_u32_e32 v182, 0x6000, v182
	s_waitcnt lgkmcnt(1)
	global_store_dwordx4 v182, v[206:209], s[8:9]
	v_add_u32_e32 v182, 0x6000, v182
	s_waitcnt lgkmcnt(0)
	global_store_dwordx4 v182, v[210:213], s[8:9]
